# v16 + sec 7.12: attention tile-loop wave-uniform flags kept in SGPRs (v_cndmask/v_cmp_ne round trips removed)
# baseline (speedup 1.0000x reference)
; #define LAS __attribute__((address_space(3)))
; #define AT_LOADK(tt) do { const unsigned ko = kgo + (unsigned)(tt) * (64 * BR * 2); ks0 = *(const u32x4*)((const char*)K + ko); ks1 = *(const u32x4*)((const char*)K + ko + 32 * BR * 2); } while (0)
; #define AT_LOADV(tt) do { const unsigned vo = vgo + (unsigned)(tt) * 128; vs0 = *(const u32x4*)((const char*)Vt + vo); vs1 = *(const u32x4*)((const char*)Vt + vo + 64 * SEQ * 2); } while (0)
; #define AT_WRITEK(buf) do { *(LAS u32x4*)(lds + (buf) * KT_BYTES + kl) = ks0; *(LAS u32x4*)(lds + (buf) * KT_BYTES + kl + 32 * KROW) = ks1; } while (0)
; #define AT_WRITEV(buf) do { \
;         *(LAS u32x2*)(lds + (buf) * VT_BYTES + vl) = (u32x2){vs0.x, vs0.y}; *(LAS u32x2*)(lds + (buf) * VT_BYTES + vl + 8) = (u32x2){vs0.z, vs0.w}; \
;         *(LAS u32x2*)(lds + (buf) * VT_BYTES + vl + 64 * VROW) = (u32x2){vs1.x, vs1.y}; *(LAS u32x2*)(lds + (buf) * VT_BYTES + vl + 64 * VROW + 8) = (u32x2){vs1.z, vs1.w}; } while (0)
; __device__ __forceinline__ void attn_unit(int b, int h, int qb, bf16_t* Q, const bf16_t* __restrict__ K, const bf16_t* __restrict__ Vt, const bf16_t* __restrict__ Z, const float* __restrict__ hg, float lam, ...
;     ...
;     for (int t = tfirst; t < NT; ++t) {
;         const int cur = t & 1; const bool more = (t + 1 < NT), active = (t <= last_w) && (t >= tlo_w), band = (64 * t + 63 > qw0);
;         const LAS unsigned char* kb = lds + cur * KT_BYTES + r32 * KROW + hi * 16;
;         const LAS unsigned char* vb = lds + AT_VOFF + cur * VT_BYTES + r32 * VROW + hi * 8;
;         if (more) AT_LOADK(t + 1);
;         __builtin_amdgcn_sched_barrier(0);
;         if (active) att_half<0>(o, lsum, qf, kb, vb, slope2, SB, 64 * t, qw0, r32, hi, band, more, ks0, ks1, lds + (cur ^ 1) * KT_BYTES + kl);
;         else if (more) AT_WRITEK(cur ^ 1);
;         __builtin_amdgcn_sched_barrier(0);
;         if (more) AT_LOADV(t + 1);
;         __builtin_amdgcn_sched_barrier(0);
;         if (active && (64 * t + 32 <= qw0 + 31)) att_half<1>(o, lsum, qf, kb, vb, slope2, SB, 64 * t + 32, qw0, r32, hi, band, more, vs0, vs1, lds + (cur ^ 1) * VT_BYTES + vl);
;         else if (more) AT_WRITEV(cur ^ 1);
.LBB0_245:
	s_add_i32 s90, s64, 1
	s_cmp_ge_i32 s90, s85
	s_cselect_b64 s[62:63], -1, 0
	s_mov_b64 s[8:9], s[62:63]
	s_and_b64 vcc, exec, s[62:63]
	s_cbranch_vccnz .LBB0_247
.LBB0_247:
	s_and_b32 s92, s64, 1
	s_cmp_le_i32 s64, s87
	s_cselect_b64 s[10:11], -1, 0
	s_cmp_ge_i32 s64, s88
	s_cselect_b64 s[64:65], -1, 0
	s_and_b64 s[64:65], s[10:11], s[64:65]
	s_add_i32 s10, s89, 63
	s_cmp_gt_i32 s10, s84
	s_cselect_b64 s[10:11], 0, -1
	s_mov_b64 s[66:67], -1
	s_andn2_b64 vcc, exec, s[64:65]
	s_cbranch_vccz .LBB0_251
	s_and_b64 vcc, exec, s[8:9]
	s_cbranch_vccnz .LBB0_250
	s_xor_b32 s66, s92, 1
	s_mulk_i32 s66, 0x4400
	v_add_u32_e32 v128, s66, v233
	s_waitcnt vmcnt(3)
	ds_write_b128 v128, v[160:163]
	s_waitcnt vmcnt(2)
	ds_write_b128 v128, v[168:171] offset:8704
	v_add_u32_e32 v128, 0x40000, v210
	v_add_u32_e32 v129, 0x60000, v210
	global_load_dwordx4 v[160:163], v128, s[38:39]
	global_load_dwordx4 v[168:171], v129, s[38:39]

; #define LAS __attribute__((address_space(3)))
; template <int HF> ...
;     ...
;     const float tb = slope2 * (float)(kvh0 + 4 * hi - qw0 - r32) - SB;
; #pragma unroll
;     for (int sub = 0; sub < 2; ++sub) {
;         f32x16 p;
; #pragma unroll
;         for (int r = 0; r < 16; ++r) p[r] = __builtin_fmaf(s2v, (float)((r & 3) + 8 * (r >> 2)), tb);
; #pragma unroll
;         for (int d0 = 0; d0 < 4; ++d0) { const bf16x8 kf = *(const LAS bf16x8*)(kb + HF * 32 * KROW + sub * 128 + d0 * 32);
;             p = __builtin_amdgcn_mfma_f32_32x32x16_bf16(kf, qf[sub][d0], p, 0, 0, 0); }
;         if (band) { const int lim = qw0 + r32 - (kvh0 + 4 * hi);
;             asm volatile("s_nop 15" : "+v"(p));
;             const float ninf = -INFINITY;
; #pragma unroll
;             for (int r = 0; r < 16; ++r) asm("v_cmp_gt_i32_e32 vcc, %2, %1\n\tv_cndmask_b32_e32 %0, %0, %3, vcc" : "+v"(p[r]) : "v"(lim), "i"((r & 3) + 8 * (r >> 2)), "v"(ninf) : "vcc"); }
.LBB0_251:
	s_mul_i32 s91, s92, 0x4400
	s_andn2_b64 vcc, exec, s[66:67]
	v_add_u32_e32 v247, s91, v235
	s_cbranch_vccnz .LBB0_259
	v_mov_b32_e32 v142, s86
	ds_read_b128 v[248:251], v247
	ds_read_b128 v[252:255], v247 offset:32
	v_add_u32_e32 v128, s89, v246
	v_cvt_f32_i32_e32 v128, v128
	v_mov_b32_e32 v129, s72
	v_add_u32_e32 v227, 32, v223
	s_and_b64 vcc, exec, s[10:11]
	v_fma_f32 v144, s86, v128, -v129
	v_fma_f32 v128, 0, v142, v144
	v_add_f32_e32 v129, v144, v142
	v_fma_f32 v131, v142, s21, v144
	v_fma_f32 v130, v142, s20, v144
	v_fma_f32 v133, v142, s23, v144
	v_fma_f32 v132, v142, s22, v144
	v_fma_f32 v135, v142, s41, v144
	v_fma_f32 v134, v142, s40, v144
	v_fma_f32 v137, v142, s43, v144
	v_fma_f32 v136, v142, s42, v144
	v_fma_f32 v139, v142, s53, v144
	v_fma_f32 v138, v142, s52, v144
	v_fma_f32 v141, v142, s59, v144
	v_fma_f32 v140, v142, s58, v144
	v_fma_f32 v143, v142, s61, v144
	v_fma_f32 v142, v142, s60, v144
	s_waitcnt vmcnt(7) lgkmcnt(1)
	s_nop 0
	v_mfma_f32_32x32x16_bf16 v[144:159], v[248:251], v[176:179], v[128:143]
	s_waitcnt vmcnt(6) lgkmcnt(0)
	v_mfma_f32_32x32x16_bf16 v[144:159], v[252:255], v[180:183], v[144:159]
	ds_read_b128 v[248:251], v247 offset:64
	ds_read_b128 v[252:255], v247 offset:96
	s_waitcnt vmcnt(5) lgkmcnt(1)
	v_mfma_f32_32x32x16_bf16 v[144:159], v[248:251], v[184:187], v[144:159]
	s_waitcnt vmcnt(4) lgkmcnt(0)
	v_mfma_f32_32x32x16_bf16 v[144:159], v[252:255], v[188:191], v[144:159]
	s_cbranch_vccnz .LBB0_254
	s_nop 15
	s_nop 0
	v_cmp_gt_i32_e32 vcc, 0, v227
	v_cndmask_b32_e32 v144, v144, v244, vcc
	s_nop 0
	v_cmp_gt_i32_e32 vcc, 1, v227
	v_cndmask_b32_e32 v145, v145, v244, vcc
	s_nop 0
	v_cmp_gt_i32_e32 vcc, 2, v227
	v_cndmask_b32_e32 v146, v146, v244, vcc
	s_nop 0
	v_cmp_gt_i32_e32 vcc, 3, v227
	v_cndmask_b32_e32 v147, v147, v244, vcc
	s_nop 0
	v_cmp_gt_i32_e32 vcc, 8, v227
	v_cndmask_b32_e32 v148, v148, v244, vcc
	s_nop 0
	v_cmp_gt_i32_e32 vcc, 9, v227
	v_cndmask_b32_e32 v149, v149, v244, vcc
	s_nop 0
	v_cmp_gt_i32_e32 vcc, 10, v227
	v_cndmask_b32_e32 v150, v150, v244, vcc
	s_nop 0
	v_cmp_gt_i32_e32 vcc, 11, v227
	v_cndmask_b32_e32 v151, v151, v244, vcc
	s_nop 0
	v_cmp_gt_i32_e32 vcc, 16, v227
	v_cndmask_b32_e32 v152, v152, v244, vcc
	s_nop 0
	v_cmp_gt_i32_e32 vcc, 17, v227
	v_cndmask_b32_e32 v153, v153, v244, vcc
	s_nop 0
	v_cmp_gt_i32_e32 vcc, 18, v227
	v_cndmask_b32_e32 v154, v154, v244, vcc
	s_nop 0
	v_cmp_gt_i32_e32 vcc, 19, v227
	v_cndmask_b32_e32 v155, v155, v244, vcc
	s_nop 0
	v_cmp_gt_i32_e32 vcc, 24, v227
	v_cndmask_b32_e32 v156, v156, v244, vcc
	s_nop 0
	v_cmp_gt_i32_e32 vcc, 25, v227
	v_cndmask_b32_e32 v157, v157, v244, vcc
	s_nop 0
	v_cmp_gt_i32_e32 vcc, 26, v227
	v_cndmask_b32_e32 v158, v158, v244, vcc
	s_nop 0
	v_cmp_gt_i32_e32 vcc, 27, v227
	v_cndmask_b32_e32 v159, v159, v244, vcc
